# idle-half CUs issue an early L2 writeback after their G3 weight conversion so the G3->G4 barrier flush is smaller
# baseline (speedup 1.0000x reference)
.LBB0_925:
	v_readlane_b32 s74, v252, 17
	v_readlane_b32 s75, v252, 18
	v_readlane_b32 s76, v252, 11
	v_readlane_b32 s77, v252, 12
	s_nop 3
	s_and_b64 s[76:77], s[76:77], exec
	s_and_b64 s[76:77], s[76:77], s[74:75]
	s_cmp_eq_u64 s[76:77], 0
	s_cbranch_scc1 .Lwb_skip
	s_waitcnt vmcnt(0)
	buffer_wbl2 sc1
	s_waitcnt vmcnt(0)
